# v22 + phase B tail: the CU partners of the 64 workgroups that run a 9th GEMM tile take no tail jobs (9th tile runs alone on its CU); tail jobs strided over the other 384
# speedup vs baseline: 1.0090x; 1.0043x over previous
.LBB0_227:
	s_cmpk_lg_i32 s92, 0x200
	s_cbranch_scc1 .Ltb_orig
	s_cmpk_lt_i32 s33, 0x1000
	s_cbranch_scc1 .Ltb_gemm
	s_cmpk_lt_i32 s33, 0x1040
	s_cbranch_scc1 .LBB0_387
	s_addk_i32 s33, 0x180
	s_addk_i32 s2, 0x180
	s_branch .Ltb_chk
.Ltb_gemm:
	s_add_i32 s33, s33, s92
	s_add_i32 s2, s2, s92
	s_cmpk_lt_i32 s33, 0x1040
	s_cbranch_scc1 .Ltb_chk
	s_cmpk_lt_i32 s94, 0x100
	s_cbranch_scc1 .Ltb_chk
	s_cmpk_lt_i32 s94, 0x140
	s_cbranch_scc1 .LBB0_387
	s_addk_i32 s33, 0xffc0
	s_addk_i32 s2, 0xffc0
	s_branch .Ltb_chk
